# FFN-up phase prologue: both tile batches issued before the first wait (one memory round trip instead of two at phase start)
# baseline (speedup 1.0000x reference)
; #define PG8_STAGE(bufoff, gbase, voff) do { _Pragma("unroll") for (int _i = 0; _i < 2; ++_i) \
;         __builtin_amdgcn_global_load_lds((const unsigned*)((const char*)(gbase) + (voff)[_i]), (LAS unsigned*)(lds + (bufoff) + ldsw + _i * 8192), 16, 0, 0); } while (0)
; #define PG8_WAIT_V(n) asm volatile("s_waitcnt vmcnt(" #n ")" ::: "memory")
; #define PG8_BAR __builtin_amdgcn_s_barrier()
; template <class Epi, class Sched>
; __device__ __forceinline__ void gemm_phase(const int tid, LAS unsigned char* lds, const int lda, const int ldb, const int K, const Sched& S, const Epi& E) {
;     ...
;     PG8_STAGE(PG8_SB(0, 0), cB, voffB); PG8_STAGE(PG8_SB(0, 1), cB + hstepB, voffB); PG8_STAGE(PG8_SA(0, 0), cA, voffA); PG8_STAGE(PG8_SA(0, 1), cA + hstepA, voffA);
;     if (wr == 1) PG8_BAR;
;     PG8_WAIT_V(2); PG8_BAR;
;     PG8_STAGE(PG8_SB(1, 0), cB + kstep, voffB); PG8_STAGE(PG8_SA(1, 0), cA + kstep, voffA); PG8_STAGE(PG8_SB(1, 1), cB + hstepB + kstep, voffB);
;     PG8_WAIT_V(6); PG8_BAR;
; __device__ __forceinline__ float row_rstd(const float* SS, int row) {
;     const f32x4* p = (const f32x4*)(SS + (size_t)row * 32);
;     float s = 0.f;
; #pragma unroll
;     for (int j = 0; j < 8; ++j) { const f32x4 a = p[j]; s += (a[0] + a[1]) + (a[2] + a[3]); }
;     return rsqrtf(s * (1.f / 1024.f) + EPS);
.LBB0_889:
	s_add_i32 m0, s29, 0x18000
	v_lshl_add_u64 v[248:249], v[70:71], 0, s[6:7]
	global_load_lds_dwordx4 v[248:249], off
	v_lshl_add_u64 v[248:249], v[68:69], 0, s[6:7]
	s_add_i32 m0, s29, 0x1a000
	s_add_i32 s58, s29, 0x8000
	s_add_i32 s59, s29, 0xa000
	global_load_lds_dwordx4 v[248:249], off
	v_lshl_add_u64 v[248:249], v[64:65], 0, s[6:7]
	s_mov_b32 m0, s58
	s_add_u32 s14, s52, 0x40080
	global_load_lds_dwordx4 v[248:249], off
	v_lshl_add_u64 v[248:249], v[66:67], 0, s[6:7]
	s_mov_b32 m0, s59
	s_addc_u32 s15, s53, 0
	global_load_lds_dwordx4 v[248:249], off
	s_add_i32 m0, s29, 0x1c000
	v_lshl_add_u64 v[248:249], s[14:15], 0, v[132:133]
	global_load_lds_dwordx4 v[248:249], off
	v_lshl_add_u64 v[248:249], s[14:15], 0, v[128:129]
	s_add_i32 m0, s29, 0x1e000
	s_nop 0
	global_load_lds_dwordx4 v[248:249], off
	s_waitcnt vmcnt(0)
	v_mov_b32_e32 v80, v60
	v_mov_b32_e32 v81, v52
	v_mov_b32_e32 v52, v61
	v_mov_b32_e32 v60, v62
	v_mov_b32_e32 v61, v54
	v_mov_b32_e32 v54, v63
	v_pk_add_f32 v[52:53], v[80:81], v[52:53]
	v_pk_add_f32 v[54:55], v[60:61], v[54:55]
	s_lshl_b32 s27, s27, 5
	v_pk_add_f32 v[52:53], v[52:53], v[54:55]
	v_mov_b32_e32 v54, v56
	v_mov_b32_e32 v55, v44
	v_mov_b32_e32 v44, v57
	v_pk_add_f32 v[44:45], v[54:55], v[44:45]
	v_mov_b32_e32 v54, v58
	v_mov_b32_e32 v55, v46
	v_mov_b32_e32 v46, v59
	v_pk_add_f32 v[46:47], v[54:55], v[46:47]
	s_and_b32 s38, s27, 0x60
	v_pk_add_f32 v[44:45], v[44:45], v[46:47]
	v_mov_b32_e32 v46, v48
	v_mov_b32_e32 v47, v36
	v_mov_b32_e32 v36, v49
	v_pk_add_f32 v[36:37], v[46:47], v[36:37]
	v_mov_b32_e32 v46, v50
	v_mov_b32_e32 v47, v38
	v_mov_b32_e32 v38, v51
	v_pk_add_f32 v[38:39], v[46:47], v[38:39]
	v_pk_add_f32 v[36:37], v[36:37], v[38:39]
	v_mov_b32_e32 v38, v40
	v_mov_b32_e32 v39, v28
	v_mov_b32_e32 v28, v41
	v_pk_add_f32 v[28:29], v[38:39], v[28:29]
	v_mov_b32_e32 v38, v42
	v_mov_b32_e32 v39, v30
	v_mov_b32_e32 v30, v43
	v_pk_add_f32 v[30:31], v[38:39], v[30:31]
	s_lshl_b32 s24, s36, 13
	v_pk_add_f32 v[28:29], v[28:29], v[30:31]
	v_mov_b32_e32 v30, v32
	v_mov_b32_e32 v31, v20
	v_mov_b32_e32 v20, v33
	v_pk_add_f32 v[20:21], v[30:31], v[20:21]
	v_mov_b32_e32 v30, v34
	v_mov_b32_e32 v31, v22
	v_mov_b32_e32 v22, v35
	v_pk_add_f32 v[22:23], v[30:31], v[22:23]
	s_lshl_b32 s39, s38, 7
	v_pk_add_f32 v[20:21], v[20:21], v[22:23]
	v_mov_b32_e32 v22, v24
	v_mov_b32_e32 v23, v16
	v_mov_b32_e32 v16, v25
	v_pk_add_f32 v[16:17], v[22:23], v[16:17]
	v_mov_b32_e32 v22, v26
	v_mov_b32_e32 v23, v18
	v_mov_b32_e32 v18, v27
	v_pk_add_f32 v[18:19], v[22:23], v[18:19]
	s_waitcnt vmcnt(2)
	s_barrier
	v_pk_add_f32 v[16:17], v[16:17], v[18:19]
	v_pk_add_f32 v[52:53], v[52:53], 0 op_sel_hi:[1,0]
	v_pk_add_f32 v[44:45], v[52:53], v[44:45]
	v_mov_b32_e32 v18, v12
	v_mov_b32_e32 v19, v4
	v_mov_b32_e32 v4, v13
	v_mov_b32_e32 v12, v14
	v_mov_b32_e32 v13, v6
	v_mov_b32_e32 v6, v15
	v_pk_add_f32 v[36:37], v[44:45], v[36:37]
	v_pk_add_f32 v[4:5], v[18:19], v[4:5]
	v_pk_add_f32 v[6:7], v[12:13], v[6:7]
	v_pk_add_f32 v[28:29], v[36:37], v[28:29]
	v_pk_add_f32 v[4:5], v[4:5], v[6:7]
	v_mov_b32_e32 v6, v8
	v_mov_b32_e32 v7, v0
	v_mov_b32_e32 v0, v9
	v_pk_add_f32 v[20:21], v[28:29], v[20:21]
	v_pk_add_f32 v[0:1], v[6:7], v[0:1]
	v_mov_b32_e32 v6, v10
	v_mov_b32_e32 v7, v2
	v_mov_b32_e32 v2, v11
	v_pk_add_f32 v[16:17], v[20:21], v[16:17]
	v_pk_add_f32 v[2:3], v[6:7], v[2:3]
	v_pk_add_f32 v[4:5], v[16:17], v[4:5]
	v_pk_add_f32 v[0:1], v[0:1], v[2:3]
	s_mov_b32 s14, 0x3a800000
	v_pk_add_f32 v[0:1], v[4:5], v[0:1]
	s_sext_i32_i16 s27, s2
	v_pk_fma_f32 v[0:1], v[0:1], s[14:15], v[170:171] op_sel_hi:[1,0,0]
	s_mov_b32 s2, 0x45800000
	v_mul_f32_e32 v2, 0x4b800000, v1
	v_cmp_gt_f32_e32 vcc, s33, v1
	v_cmp_gt_f32_e64 s[36:37], s33, v0
	v_or_b32_e32 v144, s4, v142
	v_cndmask_b32_e32 v1, v1, v2, vcc
	v_mul_f32_e32 v2, 0x4b800000, v0
	v_cndmask_b32_e64 v0, v0, v2, s[36:37]
	v_rsq_f32_e32 v1, v1
	v_rsq_f32_e32 v0, v0
	v_lshlrev_b32_e32 v145, 2, v142
	s_cmp_gt_i32 s13, 0
	s_waitcnt vmcnt(0)
	v_pk_mul_f32 v[2:3], v[0:1], s[2:3] op_sel_hi:[1,0]
	s_movk_i32 s2, 0x3c0
	v_cndmask_b32_e32 v141, v1, v3, vcc
	v_cndmask_b32_e64 v140, v0, v2, s[36:37]
	v_lshlrev_b32_e32 v1, 6, v144
	v_lshlrev_b32_e32 v2, 2, v144
	v_and_or_b32 v1, v1, s2, v75
	v_and_b32_e32 v2, 32, v2
	v_bitop3_b32 v1, v1, s24, v2 bitop3:0xde
	v_lshl_or_b32 v2, v142, 6, v75
	v_and_b32_e32 v3, 32, v145
	v_bitop3_b32 v146, s39, v2, v3 bitop3:0xf6
	v_lshlrev_b32_e32 v2, 14, v78
	v_and_b32_e32 v2, 0xffff8000, v2
	v_lshl_add_u32 v2, v77, 11, v2
	v_and_b32_e32 v3, 1, v78
	v_lshl_or_b32 v2, v3, 6, v2
	v_lshl_add_u32 v136, v79, 1, v2
	v_lshlrev_b32_e32 v2, 14, v72
	v_and_b32_e32 v2, 0xffff8000, v2
	s_cselect_b64 s[40:41], -1, 0
	s_add_i32 s61, s13, -2
	v_lshl_add_u32 v2, v73, 11, v2
	v_and_b32_e32 v3, 1, v72
	v_lshlrev_b32_e32 v0, 3, v76
	s_cmpk_lt_u32 s3, 0x100
	v_lshl_or_b32 v2, v3, 6, v2
	s_mov_b32 s60, 0
	s_cselect_b64 s[42:43], -1, 0
	v_or_b32_e32 v147, 16, v144
	v_or_b32_e32 v148, 64, v145
	v_or_b32_e32 v149, 32, v144
	v_or_b32_e32 v150, 0x80, v145
	v_or_b32_e32 v151, 48, v144
	v_or_b32_e32 v152, 0xc0, v145
	s_ashr_i32 s62, s30, 31
	v_mov_b32_e32 v137, v169
	v_lshl_add_u32 v138, v74, 1, v2
	v_mov_b32_e32 v139, v169
	v_add_u32_e32 v153, 0, v1
	s_lshl_b32 s4, s38, 1
	v_lshlrev_b32_e32 v168, 1, v0
	s_barrier
	s_branch .LBB0_892
